# speedup vs baseline: 1.0157x; 1.0109x over previous
.LBB0_99:
	v_ashrrev_i32_e32 v37, 31, v36
	v_lshl_add_u64 v[18:19], v[36:37], 4, s[10:11]
	v_lshlrev_b64 v[20:21], 11, v[36:37]
	v_lshl_add_u64 v[30:31], v[22:23], 0, v[20:21]
	global_load_dwordx4 v[18:21], v[18:19], off
	s_nop 0
	global_load_dwordx2 v[46:47], v[30:31], off
	global_load_dwordx2 v[44:45], v[30:31], off offset:512
	global_load_dwordx2 v[40:41], v[30:31], off offset:1024
	global_load_dwordx2 v[38:39], v[30:31], off offset:1536
	v_add_u32_e32 v30, s98, v36
	v_cmp_gt_i32_e32 vcc, s91, v30
	v_ashrrev_i32_e32 v31, 31, v30
	v_mov_b32_e32 v42, 0
	s_and_saveexec_b64 s[12:13], vcc
	s_cbranch_execz .LBB0_101
	v_lshl_add_u64 v[26:27], v[30:31], 4, s[10:11]
	global_load_dwordx4 v[52:55], v[26:27], off
	v_lshlrev_b64 v[26:27], 11, v[30:31]
	v_lshl_add_u64 v[34:35], v[22:23], 0, v[26:27]
	global_load_dwordx2 v[26:27], v[34:35], off
	global_load_dwordx2 v[28:29], v[34:35], off offset:512
	global_load_dwordx2 v[32:33], v[34:35], off offset:1024
	s_nop 0
	global_load_dwordx2 v[34:35], v[34:35], off offset:1536
	s_waitcnt vmcnt(4)
	v_add_f32_e32 v1, v52, v53
	v_add_f32_e32 v1, v54, v1
	v_add_f32_e32 v1, v55, v1
	v_fmamk_f32 v1, v1, 0x3a800000, v208
	v_cmp_gt_f32_e64 s[4:5], s95, v1
	v_mul_f32_e32 v56, 0x4b800000, v1
	s_nop 0
	v_cndmask_b32_e64 v1, v1, v56, s[4:5]
	v_rsq_f32_e32 v1, v1
	s_nop 0
	v_mul_f32_e32 v42, 0x45800000, v1
	v_cndmask_b32_e64 v42, v1, v42, s[4:5]

.LBB0_126:
	s_nop 7
	s_waitcnt lgkmcnt(4)
	v_cndmask_b32_e64 v46, v46, 0, s[18:19]
	v_cvt_pk_bf16_f32 v46, v46, v46
	ds_write_b16 v100, v46 offset:57888
	v_cndmask_b32_e64 v46, v47, 0, s[20:21]
	v_cvt_pk_bf16_f32 v46, v46, v46
	ds_write_b16 v100, v46 offset:58032
	v_cndmask_b32_e64 v46, v48, 0, s[22:23]
	v_cvt_pk_bf16_f32 v46, v46, v46
	ds_write_b16 v100, v46 offset:58176
	v_cndmask_b32_e64 v46, v49, 0, s[24:25]
	v_cvt_pk_bf16_f32 v46, v46, v46
	ds_write_b16 v100, v46 offset:58320
	s_mov_b64 s[46:47], 0x1000
	s_add_i32 s43, s43, -1
	v_lshl_add_u64 v[86:87], v[86:87], 0, s[96:97]
	s_cmp_eq_u32 s43, 0
	s_waitcnt lgkmcnt(8)
	v_mfma_f32_16x16x32_bf16 v[46:49], v[110:113], v[182:185], 0
	v_mfma_f32_16x16x32_bf16 v[46:49], v[114:117], v[186:189], v[46:49]
	v_mfma_f32_16x16x32_bf16 v[46:49], v[118:121], v[190:193], v[46:49]
	v_mfma_f32_16x16x32_bf16 v[46:49], v[122:125], v[194:197], v[46:49]
	s_waitcnt lgkmcnt(0)
	s_barrier
	ds_read_b128 v[142:145], v92 offset:57856
	ds_read_b128 v[146:149], v93 offset:53248
	ds_read_b128 v[150:153], v92 offset:57920
	ds_read_b128 v[154:157], v93 offset:53312
	ds_read_b128 v[158:161], v68 offset:34816
	ds_read_b128 v[162:165], v69 offset:53248
	ds_read_b128 v[166:169], v69 offset:55552
	ds_read_b128 v[170:173], v68 offset:34880
	ds_read_b128 v[174:177], v69 offset:53312
	ds_read_b128 v[178:181], v69 offset:55616
	s_waitcnt lgkmcnt(8)
	v_mfma_f32_16x16x32_bf16 v[46:49], v[142:145], v[146:149], v[46:49]
	s_waitcnt lgkmcnt(6)
	v_mfma_f32_16x16x32_bf16 v[46:49], v[150:153], v[154:157], v[46:49]
	s_waitcnt lgkmcnt(4)
	v_mfma_f32_16x16x32_bf16 v[10:13], v[158:161], v[162:165], v[10:13]
	s_waitcnt lgkmcnt(3)
	v_mfma_f32_16x16x32_bf16 v[14:17], v[158:161], v[166:169], v[14:17]
	s_waitcnt lgkmcnt(1)
	v_mfma_f32_16x16x32_bf16 v[10:13], v[170:173], v[174:177], v[10:13]
	s_waitcnt lgkmcnt(0)
	v_mfma_f32_16x16x32_bf16 v[14:17], v[170:173], v[178:181], v[14:17]
	s_nop 1
	v_bfe_u32 v50, v46, 16, 1
	v_add3_u32 v46, v46, v50, s93
	v_lshl_add_u64 v[50:51], v[66:67], 0, v[82:83]
	global_store_short_d16_hi v[50:51], v46, off
	v_bfe_u32 v46, v47, 16, 1
	v_add3_u32 v50, v47, v46, s93
	v_or_b32_e32 v46, 64, v82
	v_mov_b32_e32 v47, v83
	v_lshl_add_u64 v[46:47], v[66:67], 0, v[46:47]
	global_store_short_d16_hi v[46:47], v50, off
	v_bfe_u32 v46, v48, 16, 1
	v_add3_u32 v48, v48, v46, s93
	v_or_b32_e32 v46, 0x80, v82
	v_mov_b32_e32 v47, v83
	v_lshl_add_u64 v[46:47], v[66:67], 0, v[46:47]
	global_store_short_d16_hi v[46:47], v48, off
	v_bfe_u32 v46, v49, 16, 1
	v_add3_u32 v48, v49, v46, s93
	v_or_b32_e32 v46, 0xc0, v82
	v_mov_b32_e32 v47, v83
	v_lshl_add_u64 v[46:47], v[66:67], 0, v[46:47]
	global_store_short_d16_hi v[46:47], v48, off
	v_lshl_add_u64 v[82:83], v[82:83], 0, s[46:47]
	s_mov_b64 s[46:47], 0x10000
	v_lshl_add_u64 v[84:85], v[84:85], 0, s[46:47]
	s_mov_b64 s[46:47], 0x60000
	v_lshl_add_u64 v[88:89], v[88:89], 0, s[46:47]
	v_lshl_add_u64 v[90:91], v[90:91], 0, s[46:47]
	s_nop 1
	v_pk_mul_f32 v[12:13], v[44:45], v[12:13]
	v_pk_mul_f32 v[10:11], v[42:43], v[10:11]
	s_nop 2
	v_pk_mul_f32 v[16:17], v[44:45], v[16:17]
	v_pk_mul_f32 v[14:15], v[42:43], v[14:15]
	v_cvt_pk_bf16_f32 v42, v10, v11
	v_cvt_pk_bf16_f32 v43, v12, v13
	v_cvt_pk_bf16_f32 v45, v16, v17
	s_nop 0
	v_cvt_pk_bf16_f32 v44, v14, v15
	ds_write_b64 v94, v[42:43]
	ds_write_b64 v94, v[44:45] offset:4352
	s_waitcnt lgkmcnt(0)
	s_barrier
	s_cbranch_scc1 .LBB0_128
	s_waitcnt vmcnt(4)
	v_mov_b64_e32 v[44:45], v[8:9]
	v_mov_b64_e32 v[42:43], v[6:7]
	s_branch .LBB0_118

.LBB0_142:
	v_mov_b32_e32 v2, 0x1800
	v_mad_i64_i32 v[34:35], s[4:5], s12, v2, v[30:31]
	s_ashr_i32 s11, s10, 31
	s_lshl_b64 s[4:5], s[10:11], 16
	v_lshl_add_u64 v[36:37], v[32:33], 0, s[4:5]
	v_mov_b32_e32 v29, 0
	s_mov_b32 s13, 0
	s_waitcnt lgkmcnt(0)
	s_barrier
	s_add_u32 s20, s2, 0x9300000
	s_addc_u32 s21, s3, 0
	s_add_u32 s16, s20, 0xc000
	s_addc_u32 s17, s21, 0
	s_mov_b64 s[18:19], 0x1800
	v_lshl_add_u64 v[132:133], v[34:35], 0, s[20:21]
	v_lshl_add_u64 v[134:135], v[132:133], 0, s[18:19]
	v_lshl_add_u64 v[136:137], v[134:135], 0, s[18:19]
	v_lshl_add_u64 v[138:139], v[136:137], 0, s[18:19]
	v_lshl_add_u64 v[140:141], v[138:139], 0, s[18:19]
	v_lshl_add_u64 v[142:143], v[140:141], 0, s[18:19]
	v_lshl_add_u64 v[144:145], v[142:143], 0, s[18:19]
	v_lshl_add_u64 v[146:147], v[144:145], 0, s[18:19]
	global_load_ushort v100, v[132:133], off
	global_load_ushort v101, v[132:133], off offset:1024
	global_load_ushort v102, v[134:135], off
	global_load_ushort v103, v[134:135], off offset:1024
	global_load_ushort v104, v[136:137], off
	global_load_ushort v105, v[136:137], off offset:1024
	global_load_ushort v106, v[138:139], off
	global_load_ushort v107, v[138:139], off offset:1024
	global_load_ushort v108, v[140:141], off
	global_load_ushort v109, v[140:141], off offset:1024
	global_load_ushort v110, v[142:143], off
	global_load_ushort v111, v[142:143], off offset:1024
	global_load_ushort v112, v[144:145], off
	global_load_ushort v113, v[144:145], off offset:1024
	global_load_ushort v114, v[146:147], off
	global_load_ushort v115, v[146:147], off offset:1024
	s_waitcnt vmcnt(0)
.LBB0_143:
	v_mov_b32_e32 v116, v100
	v_mov_b32_e32 v117, v101
	v_mov_b32_e32 v74, v102
	v_mov_b32_e32 v75, v103
	v_mov_b32_e32 v76, v104
	v_mov_b32_e32 v77, v105
	v_mov_b32_e32 v78, v106
	v_mov_b32_e32 v79, v107
	v_mov_b32_e32 v80, v108
	v_mov_b32_e32 v81, v109
	v_mov_b32_e32 v82, v110
	v_mov_b32_e32 v83, v111
	v_mov_b32_e32 v84, v112
	v_mov_b32_e32 v85, v113
	v_mov_b32_e32 v86, v114
	v_mov_b32_e32 v87, v115
	v_lshl_add_u64 v[132:133], v[34:35], 0, s[16:17]
	v_lshl_add_u64 v[134:135], v[132:133], 0, s[18:19]
	v_lshl_add_u64 v[136:137], v[134:135], 0, s[18:19]
	v_lshl_add_u64 v[138:139], v[136:137], 0, s[18:19]
	v_lshl_add_u64 v[140:141], v[138:139], 0, s[18:19]
	v_lshl_add_u64 v[142:143], v[140:141], 0, s[18:19]
	v_lshl_add_u64 v[144:145], v[142:143], 0, s[18:19]
	v_lshl_add_u64 v[146:147], v[144:145], 0, s[18:19]
	global_load_ushort v100, v[132:133], off
	global_load_ushort v101, v[132:133], off offset:1024
	global_load_ushort v102, v[134:135], off
	global_load_ushort v103, v[134:135], off offset:1024
	global_load_ushort v104, v[136:137], off
	global_load_ushort v105, v[136:137], off offset:1024
	global_load_ushort v106, v[138:139], off
	global_load_ushort v107, v[138:139], off offset:1024
	global_load_ushort v108, v[140:141], off
	global_load_ushort v109, v[140:141], off offset:1024
	global_load_ushort v110, v[142:143], off
	global_load_ushort v111, v[142:143], off offset:1024
	global_load_ushort v112, v[144:145], off
	global_load_ushort v113, v[144:145], off offset:1024
	global_load_ushort v114, v[146:147], off
	global_load_ushort v115, v[146:147], off offset:1024
	s_add_i32 s4, s13, 0
	v_mov_b32_e32 v50, s4
	ds_read_b128 v[2:5], v50
	ds_read_b128 v[38:41], v50 offset:16
	ds_read_b128 v[52:55], v50 offset:32
	ds_read_b128 v[56:59], v50 offset:48
	v_lshl_add_u64 v[60:61], s[2:3], 0, v[34:35]
	s_waitcnt lgkmcnt(0)
	v_mul_f32_e32 v3, v10, v3
	v_fmac_f32_e32 v3, v8, v2
	v_fmac_f32_e32 v3, v6, v4
	v_fmac_f32_e32 v3, v18, v5
	v_add_f32_e32 v2, v1, v3
	s_waitcnt lgkmcnt(2)
	v_mul_f32_e32 v3, v11, v39
	v_fmac_f32_e32 v3, v9, v38
	v_fmac_f32_e32 v3, v7, v40
	v_fmac_f32_e32 v3, v19, v41
	v_add_f32_e32 v38, v2, v3
	s_waitcnt lgkmcnt(0)
	v_mov_b32_e32 v3, v56
	v_mov_b32_e32 v56, v53
	v_mov_b32_e32 v2, v52
	v_pk_mul_f32 v[4:5], v[14:15], v[56:57]
	s_addk_i32 s13, 0x200
	v_pk_fma_f32 v[2:3], v[12:13], v[2:3], v[4:5]
	v_mov_b32_e32 v4, v54
	v_mov_b32_e32 v5, v58
	v_pk_fma_f32 v[2:3], v[16:17], v[4:5], v[2:3]
	v_mov_b32_e32 v58, v55
	v_pk_fma_f32 v[2:3], v[20:21], v[58:59], v[2:3]
	s_cmpk_lg_i32 s13, 0x1000
	v_add_f32_e32 v2, v38, v2
	v_add_f32_e32 v2, v2, v3
	v_max_f32_e64 v3, -v2, 0
	v_mul_f32_e64 v2, |v2|, s89
	v_exp_f32_e32 v2, v2
	s_nop 0
	v_add_f32_e32 v2, 1.0, v2
	v_cmp_gt_f32_e32 vcc, s95, v2
	s_nop 1
	v_cndmask_b32_e64 v4, 0, 32, vcc
	v_ldexp_f32 v2, v2, v4
	v_log_f32_e32 v2, v2
	s_nop 0
	v_mul_f32_e32 v4, 0x3f317217, v2
	v_fma_f32 v4, v2, s92, -v4
	v_fmac_f32_e32 v4, 0x3377d1cf, v2
	v_fmac_f32_e32 v4, 0x3f317217, v2
	v_cmp_lt_f32_e64 s[4:5], |v2|, s78
	s_nop 1
	v_cndmask_b32_e64 v2, v2, v4, s[4:5]
	s_mov_b32 s4, 0x9300000
	v_cndmask_b32_e32 v4, 0, v211, vcc
	v_add_co_u32_e32 v52, vcc, s4, v60
	v_sub_f32_e32 v2, v2, v4
	s_nop 0
	v_addc_co_u32_e32 v53, vcc, 0, v61, vcc
	v_add_f32_e32 v2, v3, v2
	v_fmac_f32_e32 v29, 0xbd800000, v2
	v_mul_f32_e32 v2, 0x3fb8aa3b, v29
	v_exp_f32_e32 v2, v2
	s_mov_b32 s4, 0x9301000
	v_add_co_u32_e32 v68, vcc, s4, v60
	s_mov_b32 s4, 0x9303000
	s_nop 0
	v_addc_co_u32_e32 v69, vcc, 0, v61, vcc
	v_add_co_u32_e32 v70, vcc, s4, v60
	s_mov_b32 s4, 0x9304000
	s_nop 0
	v_addc_co_u32_e32 v71, vcc, 0, v61, vcc
	v_add_co_u32_e32 v72, vcc, s4, v60
	v_mul_f32_e32 v3, 0xbfb8aa3b, v29
	s_nop 0
	v_addc_co_u32_e32 v73, vcc, 0, v61, vcc
	s_mov_b32 s4, 0x9306000
	v_exp_f32_e32 v3, v3
	v_add_co_u32_e32 v40, vcc, s4, v60
	s_mov_b32 s4, 0x9307000
	s_nop 0
	v_addc_co_u32_e32 v41, vcc, 0, v61, vcc
	v_add_co_u32_e32 v38, vcc, s4, v60
	s_mov_b32 s4, 0x9309000
	s_nop 0
	v_addc_co_u32_e32 v39, vcc, 0, v61, vcc
	v_lshlrev_b32_e32 v4, 16, v116
	v_mul_f32_e32 v4, 0x3db504f3, v4
	v_mul_f32_e32 v2, v4, v2
	v_cvt_pk_bf16_f32 v54, v2, v2
	v_lshlrev_b32_e32 v4, 16, v117
	v_mul_f32_e32 v51, v3, v4
	v_add_co_u32_e32 v4, vcc, s4, v60
	s_mov_b32 s4, 0x930a000
	s_nop 0
	v_addc_co_u32_e32 v5, vcc, 0, v61, vcc
	v_add_co_u32_e32 v2, vcc, s4, v60
	s_nop 1
	v_addc_co_u32_e32 v3, vcc, 0, v61, vcc
	s_nop 0
	global_store_short v[52:53], v54, off
	v_cvt_pk_bf16_f32 v54, v51, v51
	global_store_short v[52:53], v54, off offset:1024
	ds_read_b128 v[52:55], v50 offset:64
	ds_read_b128 v[56:59], v50 offset:80
	ds_read_b128 v[60:63], v50 offset:96
	ds_read_b128 v[64:67], v50 offset:112
	s_waitcnt lgkmcnt(3)
	v_mul_f32_e32 v53, v10, v53
	v_fmac_f32_e32 v53, v8, v52
	v_fmac_f32_e32 v53, v6, v54
	v_fmac_f32_e32 v53, v18, v55
	v_add_f32_e32 v52, v1, v53
	s_waitcnt lgkmcnt(2)
	v_mul_f32_e32 v53, v11, v57
	v_fmac_f32_e32 v53, v9, v56
	v_fmac_f32_e32 v53, v7, v58
	v_fmac_f32_e32 v53, v19, v59
	v_add_f32_e32 v56, v52, v53
	s_waitcnt lgkmcnt(0)
	v_mov_b32_e32 v53, v64
	v_mov_b32_e32 v64, v61
	v_mov_b32_e32 v52, v60
	v_pk_mul_f32 v[54:55], v[14:15], v[64:65]
	s_nop 0
	v_pk_fma_f32 v[52:53], v[12:13], v[52:53], v[54:55]
	v_mov_b32_e32 v54, v62
	v_mov_b32_e32 v55, v66
	v_pk_fma_f32 v[52:53], v[16:17], v[54:55], v[52:53]
	v_mov_b32_e32 v66, v63
	v_pk_fma_f32 v[52:53], v[20:21], v[66:67], v[52:53]
	s_nop 0
	v_add_f32_e32 v52, v56, v52
	v_add_f32_e32 v52, v52, v53
	v_max_f32_e64 v53, -v52, 0
	v_mul_f32_e64 v52, |v52|, s89
	v_exp_f32_e32 v52, v52
	s_nop 0
	v_add_f32_e32 v52, 1.0, v52
	v_cmp_gt_f32_e32 vcc, s95, v52
	s_nop 1
	v_cndmask_b32_e64 v54, 0, 32, vcc
	v_ldexp_f32 v52, v52, v54
	v_log_f32_e32 v52, v52
	s_nop 0
	v_mul_f32_e32 v54, 0x3f317217, v52
	v_fma_f32 v54, v52, s92, -v54
	v_fmac_f32_e32 v54, 0x3377d1cf, v52
	v_fmac_f32_e32 v54, 0x3f317217, v52
	v_cmp_lt_f32_e64 s[4:5], |v52|, s78
	s_nop 1
	v_cndmask_b32_e64 v52, v52, v54, s[4:5]
	v_cndmask_b32_e32 v54, 0, v211, vcc
	v_sub_f32_e32 v52, v52, v54
	v_add_f32_e32 v52, v53, v52
	v_fmac_f32_e32 v29, 0xbd800000, v52
	v_mul_f32_e32 v52, 0x3fb8aa3b, v29
	v_exp_f32_e32 v52, v52
	v_mul_f32_e32 v53, 0xbfb8aa3b, v29
	v_exp_f32_e32 v53, v53
	v_lshlrev_b32_e32 v54, 16, v74
	v_mul_f32_e32 v54, 0x3db504f3, v54
	v_mul_f32_e32 v52, v54, v52
	v_lshlrev_b32_e32 v54, 16, v75
	v_cvt_pk_bf16_f32 v52, v52, v52
	v_mul_f32_e32 v74, v53, v54
	global_store_short v[68:69], v52, off offset:2048
	v_cvt_pk_bf16_f32 v52, v74, v74
	global_store_short v[68:69], v52, off offset:3072
	ds_read_b128 v[52:55], v50 offset:128
	s_waitcnt lgkmcnt(0)
	v_mul_f32_e32 v53, v10, v53
	v_fmac_f32_e32 v53, v8, v52
	v_fmac_f32_e32 v53, v6, v54
	v_fmac_f32_e32 v53, v18, v55
	v_add_f32_e32 v56, v1, v53
	ds_read_b128 v[52:55], v50 offset:144
	s_waitcnt lgkmcnt(0)
	v_mul_f32_e32 v53, v11, v53
	v_fmac_f32_e32 v53, v9, v52
	v_fmac_f32_e32 v53, v7, v54
	v_fmac_f32_e32 v53, v19, v55
	v_add_f32_e32 v62, v56, v53
	ds_read_b128 v[52:55], v50 offset:160
	ds_read_b128 v[56:59], v50 offset:176
	s_waitcnt lgkmcnt(1)
	v_mov_b32_e32 v60, v52
	s_waitcnt lgkmcnt(0)
	v_mov_b32_e32 v61, v56
	v_mov_b32_e32 v56, v53
	v_pk_mul_f32 v[52:53], v[14:15], v[56:57]
	v_mov_b32_e32 v56, v54
	v_pk_fma_f32 v[52:53], v[12:13], v[60:61], v[52:53]
	v_mov_b32_e32 v57, v58
	v_pk_fma_f32 v[52:53], v[16:17], v[56:57], v[52:53]
	v_mov_b32_e32 v58, v55
	v_pk_fma_f32 v[52:53], v[20:21], v[58:59], v[52:53]
	s_nop 0
	v_add_f32_e32 v52, v62, v52
	v_add_f32_e32 v52, v52, v53
	v_max_f32_e64 v53, -v52, 0
	v_mul_f32_e64 v52, |v52|, s89
	v_exp_f32_e32 v52, v52
	s_nop 0
	v_add_f32_e32 v52, 1.0, v52
	v_cmp_gt_f32_e32 vcc, s95, v52
	s_nop 1
	v_cndmask_b32_e64 v54, 0, 32, vcc
	v_ldexp_f32 v52, v52, v54
	v_log_f32_e32 v52, v52
	s_nop 0
	v_mul_f32_e32 v54, 0x3f317217, v52
	v_fma_f32 v54, v52, s92, -v54
	v_fmac_f32_e32 v54, 0x3377d1cf, v52
	v_fmac_f32_e32 v54, 0x3f317217, v52
	v_cmp_lt_f32_e64 s[4:5], |v52|, s78
	s_nop 1
	v_cndmask_b32_e64 v52, v52, v54, s[4:5]
	v_cndmask_b32_e32 v54, 0, v211, vcc
	v_sub_f32_e32 v52, v52, v54
	v_add_f32_e32 v52, v53, v52
	v_fmac_f32_e32 v29, 0xbd800000, v52
	v_mul_f32_e32 v52, 0x3fb8aa3b, v29
	v_exp_f32_e32 v52, v52
	v_mul_f32_e32 v53, 0xbfb8aa3b, v29
	v_exp_f32_e32 v53, v53
	v_lshlrev_b32_e32 v54, 16, v76
	v_mul_f32_e32 v54, 0x3db504f3, v54
	v_mul_f32_e32 v52, v54, v52
	v_lshlrev_b32_e32 v54, 16, v77
	v_cvt_pk_bf16_f32 v52, v52, v52
	v_mul_f32_e32 v75, v53, v54
	global_store_short v[70:71], v52, off
	v_cvt_pk_bf16_f32 v52, v75, v75
	global_store_short v[70:71], v52, off offset:1024
	ds_read_b128 v[52:55], v50 offset:192
	ds_read_b128 v[56:59], v50 offset:208
	s_waitcnt lgkmcnt(1)
	v_mov_b32_e32 v60, v52
	s_waitcnt lgkmcnt(0)
	v_mov_b32_e32 v61, v56
	v_mov_b32_e32 v56, v53
	v_pk_mul_f32 v[52:53], v[10:11], v[56:57]
	v_mov_b32_e32 v56, v54
	v_pk_fma_f32 v[52:53], v[8:9], v[60:61], v[52:53]
	v_mov_b32_e32 v57, v58
	v_pk_fma_f32 v[52:53], v[6:7], v[56:57], v[52:53]
	v_mov_b32_e32 v58, v55
	v_pk_fma_f32 v[52:53], v[18:19], v[58:59], v[52:53]
	s_nop 0
	v_add_f32_e32 v52, v1, v52
	v_add_f32_e32 v62, v52, v53
	ds_read_b128 v[52:55], v50 offset:224
	ds_read_b128 v[56:59], v50 offset:240
	s_waitcnt lgkmcnt(1)
	v_mov_b32_e32 v60, v52
	s_waitcnt lgkmcnt(0)
	v_mov_b32_e32 v61, v56
	v_mov_b32_e32 v56, v53
	v_pk_mul_f32 v[52:53], v[14:15], v[56:57]
	v_mov_b32_e32 v56, v54
	v_pk_fma_f32 v[52:53], v[12:13], v[60:61], v[52:53]
	v_mov_b32_e32 v57, v58
	v_pk_fma_f32 v[52:53], v[16:17], v[56:57], v[52:53]
	v_mov_b32_e32 v58, v55
	v_pk_fma_f32 v[52:53], v[20:21], v[58:59], v[52:53]
	s_nop 0
	v_add_f32_e32 v52, v62, v52
	v_add_f32_e32 v52, v52, v53
	v_max_f32_e64 v53, -v52, 0
	v_mul_f32_e64 v52, |v52|, s89
	v_exp_f32_e32 v52, v52
	s_nop 0
	v_add_f32_e32 v52, 1.0, v52
	v_cmp_gt_f32_e32 vcc, s95, v52
	s_nop 1
	v_cndmask_b32_e64 v54, 0, 32, vcc
	v_ldexp_f32 v52, v52, v54
	v_log_f32_e32 v52, v52
	s_nop 0
	v_mul_f32_e32 v54, 0x3f317217, v52
	v_fma_f32 v54, v52, s92, -v54
	v_fmac_f32_e32 v54, 0x3377d1cf, v52
	v_fmac_f32_e32 v54, 0x3f317217, v52
	v_cmp_lt_f32_e64 s[4:5], |v52|, s78
	s_nop 1
	v_cndmask_b32_e64 v52, v52, v54, s[4:5]
	v_cndmask_b32_e32 v54, 0, v211, vcc
	v_sub_f32_e32 v52, v52, v54
	v_add_f32_e32 v52, v53, v52
	v_fmac_f32_e32 v29, 0xbd800000, v52
	v_mul_f32_e32 v52, 0x3fb8aa3b, v29
	v_exp_f32_e32 v52, v52
	v_mul_f32_e32 v53, 0xbfb8aa3b, v29
	v_exp_f32_e32 v53, v53
	v_lshlrev_b32_e32 v54, 16, v78
	v_mul_f32_e32 v54, 0x3db504f3, v54
	v_mul_f32_e32 v52, v54, v52
	v_lshlrev_b32_e32 v54, 16, v79
	v_cvt_pk_bf16_f32 v52, v52, v52
	v_mul_f32_e32 v70, v53, v54
	global_store_short v[72:73], v52, off offset:2048
	v_cvt_pk_bf16_f32 v52, v70, v70
	global_store_short v[72:73], v52, off offset:3072
	ds_read_b128 v[52:55], v50 offset:256
	ds_read_b128 v[56:59], v50 offset:272
	ds_read_b128 v[60:63], v50 offset:288
	ds_read_b128 v[64:67], v50 offset:304
	s_waitcnt lgkmcnt(3)
	v_mov_b32_e32 v68, v52
	s_waitcnt lgkmcnt(2)
	v_mov_b32_e32 v69, v56
	v_mov_b32_e32 v56, v53
	v_pk_mul_f32 v[52:53], v[10:11], v[56:57]
	v_mov_b32_e32 v56, v54
	v_pk_fma_f32 v[52:53], v[8:9], v[68:69], v[52:53]
	v_mov_b32_e32 v57, v58
	v_pk_fma_f32 v[52:53], v[6:7], v[56:57], v[52:53]
	v_mov_b32_e32 v58, v55
	v_pk_fma_f32 v[52:53], v[18:19], v[58:59], v[52:53]
	s_nop 0
	v_add_f32_e32 v52, v1, v52
	v_add_f32_e32 v56, v52, v53
	s_waitcnt lgkmcnt(0)
	v_mov_b32_e32 v53, v64
	v_mov_b32_e32 v64, v61
	v_mov_b32_e32 v52, v60
	v_pk_mul_f32 v[54:55], v[14:15], v[64:65]
	s_nop 0
	v_pk_fma_f32 v[52:53], v[12:13], v[52:53], v[54:55]
	v_mov_b32_e32 v54, v62
	v_mov_b32_e32 v55, v66
	v_pk_fma_f32 v[52:53], v[16:17], v[54:55], v[52:53]
	v_mov_b32_e32 v66, v63
	v_pk_fma_f32 v[52:53], v[20:21], v[66:67], v[52:53]
	s_nop 0
	v_add_f32_e32 v52, v56, v52
	v_add_f32_e32 v52, v52, v53
	v_max_f32_e64 v53, -v52, 0
	v_mul_f32_e64 v52, |v52|, s89
	v_exp_f32_e32 v52, v52
	s_nop 0
	v_add_f32_e32 v52, 1.0, v52
	v_cmp_gt_f32_e32 vcc, s95, v52
	s_nop 1
	v_cndmask_b32_e64 v54, 0, 32, vcc
	v_ldexp_f32 v52, v52, v54
	v_log_f32_e32 v52, v52
	s_nop 0
	v_mul_f32_e32 v54, 0x3f317217, v52
	v_fma_f32 v54, v52, s92, -v54
	v_fmac_f32_e32 v54, 0x3377d1cf, v52
	v_fmac_f32_e32 v54, 0x3f317217, v52
	v_cmp_lt_f32_e64 s[4:5], |v52|, s78
	s_nop 1
	v_cndmask_b32_e64 v52, v52, v54, s[4:5]
	v_cndmask_b32_e32 v54, 0, v211, vcc
	v_sub_f32_e32 v52, v52, v54
	v_add_f32_e32 v52, v53, v52
	v_fmac_f32_e32 v29, 0xbd800000, v52
	v_mul_f32_e32 v52, 0x3fb8aa3b, v29
	v_exp_f32_e32 v52, v52
	v_mul_f32_e32 v53, 0xbfb8aa3b, v29
	v_exp_f32_e32 v53, v53
	v_lshlrev_b32_e32 v54, 16, v80
	v_mul_f32_e32 v54, 0x3db504f3, v54
	v_mul_f32_e32 v52, v54, v52
	v_lshlrev_b32_e32 v54, 16, v81
	v_cvt_pk_bf16_f32 v52, v52, v52
	v_mul_f32_e32 v68, v53, v54
	global_store_short v[40:41], v52, off
	v_cvt_pk_bf16_f32 v52, v68, v68
	global_store_short v[40:41], v52, off offset:1024
	ds_read_b128 v[52:55], v50 offset:320
	ds_read_b128 v[56:59], v50 offset:336
	ds_read_b128 v[60:63], v50 offset:352
	ds_read_b128 v[64:67], v50 offset:368
	s_waitcnt lgkmcnt(3)
	v_mov_b32_e32 v40, v52
	s_waitcnt lgkmcnt(2)
	v_mov_b32_e32 v41, v56
	v_mov_b32_e32 v56, v53
	v_pk_mul_f32 v[52:53], v[10:11], v[56:57]
	s_nop 0
	v_pk_fma_f32 v[40:41], v[8:9], v[40:41], v[52:53]
	v_mov_b32_e32 v52, v54
	v_mov_b32_e32 v53, v58
	v_pk_fma_f32 v[40:41], v[6:7], v[52:53], v[40:41]
	v_mov_b32_e32 v58, v55
	v_pk_fma_f32 v[40:41], v[18:19], v[58:59], v[40:41]
	s_nop 0
	v_add_f32_e32 v40, v1, v40
	v_add_f32_e32 v54, v40, v41
	s_waitcnt lgkmcnt(0)
	v_mov_b32_e32 v41, v64
	v_mov_b32_e32 v64, v61
	v_mov_b32_e32 v40, v60
	v_pk_mul_f32 v[52:53], v[14:15], v[64:65]
	s_nop 0
	v_pk_fma_f32 v[40:41], v[12:13], v[40:41], v[52:53]
	v_mov_b32_e32 v52, v62
	v_mov_b32_e32 v53, v66
	v_pk_fma_f32 v[40:41], v[16:17], v[52:53], v[40:41]
	v_mov_b32_e32 v66, v63
	v_pk_fma_f32 v[40:41], v[20:21], v[66:67], v[40:41]
	s_nop 0
	v_add_f32_e32 v40, v54, v40
	v_add_f32_e32 v40, v40, v41
	v_max_f32_e64 v41, -v40, 0
	v_mul_f32_e64 v40, |v40|, s89
	v_exp_f32_e32 v40, v40
	s_nop 0
	v_add_f32_e32 v40, 1.0, v40
	v_cmp_gt_f32_e32 vcc, s95, v40
	s_nop 1
	v_cndmask_b32_e64 v52, 0, 32, vcc
	v_ldexp_f32 v40, v40, v52
	v_log_f32_e32 v40, v40
	s_nop 0
	v_mul_f32_e32 v52, 0x3f317217, v40
	v_fma_f32 v52, v40, s92, -v52
	v_fmac_f32_e32 v52, 0x3377d1cf, v40
	v_fmac_f32_e32 v52, 0x3f317217, v40
	v_cmp_lt_f32_e64 s[4:5], |v40|, s78
	s_nop 1
	v_cndmask_b32_e64 v40, v40, v52, s[4:5]
	v_cndmask_b32_e32 v52, 0, v211, vcc
	v_sub_f32_e32 v40, v40, v52
	v_add_f32_e32 v40, v41, v40
	v_fmac_f32_e32 v29, 0xbd800000, v40
	v_mul_f32_e32 v40, 0x3fb8aa3b, v29
	v_exp_f32_e32 v40, v40
	v_mul_f32_e32 v41, 0xbfb8aa3b, v29
	v_exp_f32_e32 v41, v41
	v_lshlrev_b32_e32 v52, 16, v82
	v_mul_f32_e32 v52, 0x3db504f3, v52
	v_mul_f32_e32 v40, v52, v40
	v_lshlrev_b32_e32 v52, 16, v83
	v_cvt_pk_bf16_f32 v40, v40, v40
	v_mul_f32_e32 v66, v41, v52
	global_store_short v[38:39], v40, off offset:2048
	v_cvt_pk_bf16_f32 v40, v66, v66
	global_store_short v[38:39], v40, off offset:3072
	ds_read_b128 v[38:41], v50 offset:384
	ds_read_b128 v[52:55], v50 offset:400
	ds_read_b128 v[56:59], v50 offset:416
	ds_read_b128 v[60:63], v50 offset:432
	s_waitcnt lgkmcnt(3)
	v_mov_b32_e32 v64, v38
	s_waitcnt lgkmcnt(2)
	v_mov_b32_e32 v65, v52
	v_mov_b32_e32 v52, v39
	v_pk_mul_f32 v[38:39], v[10:11], v[52:53]
	v_mov_b32_e32 v52, v40
	v_pk_fma_f32 v[38:39], v[8:9], v[64:65], v[38:39]
	v_mov_b32_e32 v53, v54
	v_pk_fma_f32 v[38:39], v[6:7], v[52:53], v[38:39]
	v_mov_b32_e32 v54, v41
	v_pk_fma_f32 v[38:39], v[18:19], v[54:55], v[38:39]
	s_nop 0
	v_add_f32_e32 v38, v1, v38
	v_add_f32_e32 v52, v38, v39
	s_waitcnt lgkmcnt(0)
	v_mov_b32_e32 v39, v60
	v_mov_b32_e32 v60, v57
	v_mov_b32_e32 v38, v56
	v_pk_mul_f32 v[40:41], v[14:15], v[60:61]
	s_nop 0
	v_pk_fma_f32 v[38:39], v[12:13], v[38:39], v[40:41]
	v_mov_b32_e32 v40, v58
	v_mov_b32_e32 v41, v62
	v_pk_fma_f32 v[38:39], v[16:17], v[40:41], v[38:39]
	v_mov_b32_e32 v62, v59
	v_pk_fma_f32 v[38:39], v[20:21], v[62:63], v[38:39]
	s_nop 0
	v_add_f32_e32 v38, v52, v38
	v_add_f32_e32 v38, v38, v39
	v_max_f32_e64 v39, -v38, 0
	v_mul_f32_e64 v38, |v38|, s89
	v_exp_f32_e32 v38, v38
	s_nop 0
	v_add_f32_e32 v38, 1.0, v38
	v_cmp_gt_f32_e32 vcc, s95, v38
	s_nop 1
	v_cndmask_b32_e64 v40, 0, 32, vcc
	v_ldexp_f32 v38, v38, v40
	v_log_f32_e32 v38, v38
	s_nop 0
	v_mul_f32_e32 v40, 0x3f317217, v38
	v_fma_f32 v40, v38, s92, -v40
	v_fmac_f32_e32 v40, 0x3377d1cf, v38
	v_fmac_f32_e32 v40, 0x3f317217, v38
	v_cmp_lt_f32_e64 s[4:5], |v38|, s78
	s_nop 1
	v_cndmask_b32_e64 v38, v38, v40, s[4:5]
	v_cndmask_b32_e32 v40, 0, v211, vcc
	v_sub_f32_e32 v38, v38, v40
	v_add_f32_e32 v38, v39, v38
	v_fmac_f32_e32 v29, 0xbd800000, v38
	v_mul_f32_e32 v38, 0x3fb8aa3b, v29
	v_exp_f32_e32 v38, v38
	v_mul_f32_e32 v39, 0xbfb8aa3b, v29
	v_exp_f32_e32 v39, v39
	v_lshlrev_b32_e32 v40, 16, v84
	v_mul_f32_e32 v40, 0x3db504f3, v40
	v_mul_f32_e32 v38, v40, v38
	v_lshlrev_b32_e32 v40, 16, v85
	v_cvt_pk_bf16_f32 v38, v38, v38
	v_mul_f32_e32 v64, v39, v40
	global_store_short v[4:5], v38, off
	v_cvt_pk_bf16_f32 v38, v64, v64
	global_store_short v[4:5], v38, off offset:1024
	ds_read_b128 v[38:41], v50 offset:448
	ds_read_b128 v[52:55], v50 offset:464
	ds_read_b128 v[56:59], v50 offset:480
	ds_read_b128 v[60:63], v50 offset:496
	s_waitcnt lgkmcnt(3)
	v_mov_b32_e32 v4, v38
	s_waitcnt lgkmcnt(2)
	v_mov_b32_e32 v5, v52
	v_mov_b32_e32 v52, v39
	v_pk_mul_f32 v[38:39], v[10:11], v[52:53]
	s_nop 0
	v_pk_fma_f32 v[4:5], v[8:9], v[4:5], v[38:39]
	v_mov_b32_e32 v38, v40
	v_mov_b32_e32 v39, v54
	v_pk_fma_f32 v[4:5], v[6:7], v[38:39], v[4:5]
	v_mov_b32_e32 v54, v41
	v_pk_fma_f32 v[4:5], v[18:19], v[54:55], v[4:5]
	s_nop 0
	v_add_f32_e32 v4, v1, v4
	v_add_f32_e32 v40, v4, v5
	s_waitcnt lgkmcnt(0)
	v_mov_b32_e32 v5, v60
	v_mov_b32_e32 v60, v57
	v_mov_b32_e32 v4, v56
	v_pk_mul_f32 v[38:39], v[14:15], v[60:61]
	s_nop 0
	v_pk_fma_f32 v[4:5], v[12:13], v[4:5], v[38:39]
	v_mov_b32_e32 v38, v58
	v_mov_b32_e32 v39, v62
	v_pk_fma_f32 v[4:5], v[16:17], v[38:39], v[4:5]
	v_mov_b32_e32 v62, v59
	v_pk_fma_f32 v[4:5], v[20:21], v[62:63], v[4:5]
	v_lshlrev_b32_e32 v39, 16, v87
	v_add_f32_e32 v4, v40, v4
	v_add_f32_e32 v4, v4, v5
	v_max_f32_e64 v5, -v4, 0
	v_mul_f32_e64 v4, |v4|, s89
	v_exp_f32_e32 v4, v4
	v_lshl_add_u64 v[40:41], s[2:3], 0, v[36:37]
	v_lshl_add_u64 v[36:37], v[36:37], 0, 16
	v_add_f32_e32 v4, 1.0, v4
	v_cmp_gt_f32_e32 vcc, s95, v4
	s_nop 1
	v_cndmask_b32_e64 v38, 0, 32, vcc
	v_ldexp_f32 v4, v4, v38
	v_log_f32_e32 v4, v4
	s_nop 0
	v_mul_f32_e32 v38, 0x3f317217, v4
	v_fma_f32 v38, v4, s92, -v38
	v_fmac_f32_e32 v38, 0x3377d1cf, v4
	v_fmac_f32_e32 v38, 0x3f317217, v4
	v_cmp_lt_f32_e64 s[4:5], |v4|, s78
	s_nop 1
	v_cndmask_b32_e64 v4, v4, v38, s[4:5]
	v_cndmask_b32_e32 v38, 0, v211, vcc
	v_sub_f32_e32 v4, v4, v38
	v_add_f32_e32 v4, v5, v4
	v_fmac_f32_e32 v29, 0xbd800000, v4
	v_mul_f32_e32 v4, 0x3fb8aa3b, v29
	v_exp_f32_e32 v38, v4
	v_mul_f32_e32 v4, 0xbfb8aa3b, v29
	v_exp_f32_e32 v4, v4
	v_lshlrev_b32_e32 v5, 16, v86
	v_mul_f32_e32 v5, 0x3db504f3, v5
	v_mul_f32_e32 v5, v5, v38
	v_mul_f32_e32 v39, v4, v39
	v_cvt_pk_bf16_f32 v4, v5, v5
	s_mov_b64 s[4:5], 0xc000
	global_store_short v[2:3], v4, off offset:2048
	v_cvt_pk_bf16_f32 v4, v39, v39
	v_lshl_add_u64 v[34:35], v[34:35], 0, s[4:5]
	global_store_short v[2:3], v4, off offset:3072
	v_cvt_pk_bf16_f32 v2, v51, v74
	v_cvt_pk_bf16_f32 v3, v75, v70
	v_cvt_pk_bf16_f32 v4, v68, v66
	v_cvt_pk_bf16_f32 v5, v64, v39
	global_store_dwordx4 v[40:41], v[2:5], off
	s_waitcnt vmcnt(17)
	s_cbranch_scc1 .LBB0_143
	s_lshl_b64 s[4:5], s[10:11], 11
	s_add_i32 s10, s10, s73
	s_add_i32 s12, s12, s87
	v_lshl_add_u64 v[2:3], v[22:23], 0, s[4:5]
	s_cmpk_gt_i32 s10, 0x1ff
	v_add_u32_e32 v28, s87, v28
	global_store_dword v[2:3], v38, off
	s_barrier
	s_cbranch_scc0 .LBB0_138

.LBB0_154:
	s_and_b64 vcc, exec, s[2:3]
	s_cbranch_vccz .LBB0_341
	s_cmp_lt_i32 s99, 14
	s_mov_b64 s[34:35], -1
	s_cbranch_scc0 .LBB0_341
	v_mbcnt_lo_u32_b32 v1, -1, 0
	v_mbcnt_hi_u32_b32 v1, -1, v1
	s_waitcnt lgkmcnt(0)
	s_load_dwordx8 s[4:11], s[76:77], 0x90
	v_and_b32_e32 v2, 63, v1
	v_lshlrev_b32_e32 v3, 2, v2
	s_waitcnt lgkmcnt(0)
	global_load_dword v4, v3, s[4:5]
	global_load_dword v5, v3, s[6:7]
	global_load_dword v6, v3, s[8:9]
	global_load_dword v7, v3, s[10:11]
	v_and_b32_e32 v3, 64, v209
	v_xor_b32_e32 v8, 1, v209
	v_add_u32_e32 v14, 64, v3
	v_cmp_lt_i32_e32 vcc, v8, v14
	v_xor_b32_e32 v9, 2, v209
	v_xor_b32_e32 v10, 4, v209
	v_cndmask_b32_e32 v8, v209, v8, vcc
	v_lshlrev_b32_e32 v131, 2, v8
	v_cmp_lt_i32_e32 vcc, v9, v14
	v_xor_b32_e32 v11, 8, v209
	v_xor_b32_e32 v12, 16, v209
	v_cndmask_b32_e32 v9, v209, v9, vcc
	v_lshlrev_b32_e32 v141, 2, v9
	v_cmp_lt_i32_e32 vcc, v10, v14
	v_xor_b32_e32 v13, 32, v209
	v_readlane_b32 s4, v254, 39
	s_waitcnt vmcnt(0)
	v_mul_f32_e32 v8, v4, v5
	ds_bpermute_b32 v8, v131, v8
	s_waitcnt vmcnt(0)
	v_mul_f32_e32 v15, v6, v7
	ds_bpermute_b32 v15, v131, v15
	v_add_u32_e32 v3, s4, v1
	v_readlane_b32 s4, v254, 5
	s_waitcnt lgkmcnt(1)
	v_fmac_f32_e32 v8, v4, v5
	ds_bpermute_b32 v4, v141, v8
	s_waitcnt lgkmcnt(1)
	v_fmac_f32_e32 v15, v6, v7
	ds_bpermute_b32 v5, v141, v15
	v_cndmask_b32_e32 v6, v209, v10, vcc
	v_lshlrev_b32_e32 v143, 2, v6
	s_waitcnt lgkmcnt(1)
	v_add_f32_e32 v4, v8, v4
	ds_bpermute_b32 v6, v143, v4
	s_waitcnt lgkmcnt(1)
	v_add_f32_e32 v5, v15, v5
	ds_bpermute_b32 v7, v143, v5
	v_cmp_lt_i32_e32 vcc, v11, v14
	v_readlane_b32 s5, v254, 6
	s_waitcnt lgkmcnt(1)
	v_add_f32_e32 v4, v4, v6
	v_cndmask_b32_e32 v8, v209, v11, vcc
	v_lshlrev_b32_e32 v145, 2, v8
	s_waitcnt lgkmcnt(0)
	v_add_f32_e32 v5, v5, v7
	ds_bpermute_b32 v6, v145, v4
	ds_bpermute_b32 v7, v145, v5
	v_cmp_lt_i32_e32 vcc, v12, v14
	v_readfirstlane_b32 s6, v3
	s_waitcnt lgkmcnt(1)
	v_add_f32_e32 v4, v4, v6
	v_cndmask_b32_e32 v8, v209, v12, vcc
	v_lshlrev_b32_e32 v147, 2, v8
	s_waitcnt lgkmcnt(0)
	v_add_f32_e32 v5, v5, v7
	ds_bpermute_b32 v6, v147, v4
	ds_bpermute_b32 v7, v147, v5
	v_cmp_lt_i32_e32 vcc, v13, v14
	s_waitcnt lgkmcnt(1)
	v_add_f32_e32 v4, v4, v6
	v_cndmask_b32_e32 v8, v209, v13, vcc
	v_lshlrev_b32_e32 v8, 2, v8
	s_waitcnt lgkmcnt(0)
	v_add_f32_e32 v5, v5, v7
	ds_bpermute_b32 v6, v8, v4
	ds_bpermute_b32 v7, v8, v5
	s_andn2_b64 vcc, exec, s[4:5]
	s_cbranch_vccnz .LBB0_383
	s_waitcnt lgkmcnt(1)
	v_add_f32_e32 v4, v4, v6
	s_waitcnt lgkmcnt(0)
	v_add_f32_e32 v5, v5, v7
	s_load_dwordx2 s[2:3], s[76:77], 0xe8
	v_mul_f32_e32 v4, 0x3fb8aa3b, v4
	v_mul_f32_e32 v5, 0x3fb8aa3b, v5
	v_exp_f32_e32 v4, v4
	v_exp_f32_e32 v5, v5
	s_waitcnt lgkmcnt(0)
	s_add_u32 s0, s2, 0x9300000
	v_lshlrev_b32_e32 v6, 4, v2
	v_writelane_b32 v255, s0, 2
	v_sub_f32_e32 v4, v4, v5
	s_addc_u32 s0, s3, 0
	v_add_f32_e32 v151, 0x3eb60549, v4
	v_lshlrev_b32_e32 v4, 3, v2
	v_and_b32_e32 v6, 0xc0, v6
	v_lshlrev_b32_e32 v7, 1, v2
	s_add_i32 s96, 0, 0x10000
	v_and_or_b32 v6, v4, 24, v6
	v_and_b32_e32 v7, 32, v7
	v_and_b32_e32 v4, 0x100, v4
	s_cmp_lg_u32 s96, -1
	v_or3_b32 v4, v6, v7, v4
	s_cselect_b32 s4, s96, 0
	v_lshlrev_b32_e32 v6, 3, v1
	v_ashrrev_i32_e32 v5, 4, v3
	v_add_u32_e32 v153, s4, v4
	v_and_b32_e32 v4, 0x78, v6
	v_lshlrev_b32_e32 v8, 1, v4
	v_and_b32_e32 v3, 0x70, v3
	v_lshlrev_b32_e32 v9, 8, v5
	v_bitop3_b32 v9, v8, v9, v3 bitop3:0xde
	v_add_u32_e32 v3, 32, v5
	v_lshlrev_b32_e32 v10, 1, v3
	v_and_b32_e32 v3, 0xfffff0, v3
	v_and_or_b32 v3, v10, 8, v3
	v_lshrrev_b32_e32 v3, 1, v3
	v_bfe_u32 v6, v6, 5, 2
	v_lshrrev_b32_e32 v10, 1, v5
	v_and_b32_e32 v11, 3, v5
	v_or_b32_e32 v3, v3, v6
	v_and_or_b32 v10, v10, 4, v11
	v_lshlrev_b32_e32 v3, 9, v3
	v_lshlrev_b32_e32 v10, 6, v10
	v_and_b32_e32 v8, 48, v8
	v_or3_b32 v155, v3, v10, v8
	v_lshlrev_b32_e32 v3, 1, v5
	v_and_b32_e32 v11, 0xfffff0, v5
	v_and_or_b32 v3, v3, 8, v11
	v_lshrrev_b32_e32 v3, 1, v3
	s_and_b32 s4, s6, 0x3fffffc0
	v_or_b32_e32 v3, v3, v6
	s_lshl_b32 s4, s4, 2
	v_lshlrev_b32_e32 v3, 9, v3
	v_writelane_b32 v255, s0, 3
	s_add_i32 s4, s4, 0
	v_or3_b32 v157, v3, v10, v8
	s_movk_i32 s0, 0x1800
	v_add_u32_e32 v3, 64, v5
	s_add_i32 s10, s4, 0x20000
	s_bfe_u32 s11, s6, 0x10006
	v_mad_i64_i32 v[132:133], s[4:5], v5, s0, 0
	v_mad_i64_i32 v[134:135], s[4:5], v3, s0, 0
	s_lshl_b32 s4, s11, 7
	v_and_b32_e32 v149, 31, v1
	v_lshrrev_b32_e32 v7, 5, v2
	s_add_i32 s4, s4, 0
	s_ashr_i32 s7, s6, 7
	v_lshlrev_b32_e32 v8, 4, v7
	v_lshlrev_b32_e32 v3, 4, v1
	v_lshl_add_u32 v11, v149, 8, s4
	s_movk_i32 s4, 0x70
	s_lshl_b32 s97, s7, 5
	v_and_b32_e32 v10, 0x70, v3
	v_bitop3_b32 v12, v8, v3, s4 bitop3:0x78
	s_movk_i32 s4, 0x60
	s_lshl_b32 s7, s7, 14
	s_lshl_b32 s12, s11, 6
	v_bitop3_b32 v13, v8, v10, 32 bitop3:0x36
	v_bitop3_b32 v14, v8, v10, 64 bitop3:0x36
	v_bitop3_b32 v10, v8, v10, s4 bitop3:0x36
	v_cmp_gt_u32_e64 s[4:5], 32, v2
	v_lshlrev_b32_e32 v2, 2, v149
	s_add_i32 s7, s7, 0
	s_and_b32 s6, 64, s6
	v_add_u32_e32 v159, s10, v2
	v_add_u32_e32 v3, 0x80, v5
	s_cmp_eq_u32 s11, 0
	v_add_u32_e32 v5, s7, v2
	v_and_b32_e32 v2, 1, v1
	v_mad_i64_i32 v[136:137], s[8:9], v3, s0, 0
	s_cselect_b64 s[82:83], -1, 0
	s_cmp_lg_u32 s6, 0
	v_cmp_eq_u32_e64 s[6:7], 0, v2
	v_lshlrev_b32_e32 v2, 1, v149
	v_mov_b32_e32 v3, v0
	v_lshlrev_b32_e32 v130, 2, v7
	v_lshl_add_u64 v[2:3], s[2:3], 0, v[2:3]
	s_mov_b64 s[8:9], 0x15300000
	v_and_b32_e32 v1, 15, v1
	s_cselect_b64 s[76:77], -1, 0
	v_lshl_add_u64 v[138:139], v[2:3], 0, s[8:9]
	v_or_b32_e32 v140, 1, v130
	v_or_b32_e32 v142, 2, v130
	v_or_b32_e32 v144, 3, v130
	v_or_b32_e32 v146, 8, v130
	v_or_b32_e32 v148, 9, v130
	v_or_b32_e32 v150, 10, v130
	v_or_b32_e32 v152, 11, v130
	v_or_b32_e32 v154, 16, v130
	v_or_b32_e32 v156, 17, v130
	v_or_b32_e32 v158, 18, v130
	v_or_b32_e32 v160, 19, v130
	v_or_b32_e32 v162, 24, v130
	v_or_b32_e32 v164, 25, v130
	v_or_b32_e32 v166, 26, v130
	v_or_b32_e32 v168, 27, v130
	v_lshl_or_b32 v2, v1, 4, v132
	v_mov_b32_e32 v3, v133
	s_lshl_b32 s0, s12, 1
	v_lshlrev_b32_e32 v6, 3, v7
	v_add_u32_e32 v161, s10, v8
	v_lshl_add_u32 v163, v7, 11, v5
	v_lshlrev_b32_e32 v7, 9, v140
	v_lshlrev_b32_e32 v8, 9, v142
	v_lshlrev_b32_e32 v15, 9, v144
	v_lshlrev_b32_e32 v16, 9, v146
	v_lshlrev_b32_e32 v17, 9, v148
	v_lshlrev_b32_e32 v18, 9, v150
	v_lshlrev_b32_e32 v19, 9, v152
	v_lshlrev_b32_e32 v20, 9, v154
	v_lshlrev_b32_e32 v21, 9, v156
	v_lshlrev_b32_e32 v22, 9, v158
	v_lshlrev_b32_e32 v23, 9, v160
	v_lshlrev_b32_e32 v24, 9, v162
	v_lshlrev_b32_e32 v25, 9, v164
	v_lshlrev_b32_e32 v26, 9, v166
	v_lshlrev_b32_e32 v27, 9, v168
	v_lshl_add_u64 v[2:3], s[2:3], 0, v[2:3]
	s_mov_b64 s[2:3], 0x9571000
	v_writelane_b32 v255, s0, 4
	v_lshl_add_u64 v[170:171], v[2:3], 0, s[2:3]
	v_lshlrev_b32_e32 v172, 1, v6
	v_lshlrev_b32_e32 v174, 1, v4
	v_add_u32_e32 v165, v5, v7
	v_add_u32_e32 v167, v5, v8
	v_add_u32_e32 v169, v5, v15
	v_add_u32_e32 v202, v5, v16
	v_add_u32_e32 v203, v5, v17
	v_add_u32_e32 v204, v5, v18
	v_add_u32_e32 v205, v5, v19
	v_add_u32_e32 v216, v5, v20
	v_add_u32_e32 v217, v5, v21
	v_add_u32_e32 v218, v5, v22
	v_add_u32_e32 v219, v5, v23
	v_add_u32_e32 v220, v5, v24
	v_add_u32_e32 v221, v5, v25
	v_add_u32_e32 v222, v5, v26
	v_add_u32_e32 v223, v5, v27
	v_add_u32_e32 v224, 0, v9
	v_add_u32_e32 v225, v11, v12
	v_add_u32_e32 v226, v11, v13
	v_add_u32_e32 v227, v11, v14
	v_add_u32_e32 v228, v11, v10
	v_bfe_u32 v250, v224, 11, 1
	v_bfe_u32 v251, v149, 3, 1
	v_lshlrev_b32_e32 v250, 7, v250
	v_lshlrev_b32_e32 v251, 7, v251
	v_xor_b32_e32 v224, v224, v250
	v_xor_b32_e32 v225, v225, v251
	v_xor_b32_e32 v226, v226, v251
	v_xor_b32_e32 v227, v227, v251
	v_xor_b32_e32 v228, v228, v251
	v_readlane_b32 s0, v254, 33
	v_readlane_b32 s94, v254, 53
	v_writelane_b32 v255, s73, 5
	s_branch .LBB0_159

.LBB0_164:
	v_mov_b32_e32 v14, v0
	v_mov_b32_e32 v15, v0
	v_sub_u32_e32 v231, v1, v130
	v_mov_b32_e32 v1, v0
	v_mov_b32_e32 v2, v0
	v_mov_b32_e32 v3, v0
	v_mov_b32_e32 v4, v0
	v_mov_b32_e32 v5, v0
	v_mov_b32_e32 v6, v0
	v_mov_b32_e32 v7, v0
	v_mov_b32_e32 v8, v0
	v_mov_b32_e32 v9, v0
	v_mov_b32_e32 v10, v0
	v_mov_b32_e32 v11, v0
	v_mov_b32_e32 v12, v0
	v_mov_b32_e32 v13, v0
	v_mov_b64_e32 v[64:65], v[14:15]
	v_mov_b64_e32 v[48:49], v[14:15]
	v_mov_b64_e32 v[32:33], v[14:15]
	s_lshl_b32 s33, s10, 1
	v_mov_b64_e32 v[62:63], v[12:13]
	v_mov_b64_e32 v[60:61], v[10:11]
	v_mov_b64_e32 v[58:59], v[8:9]
	v_mov_b64_e32 v[56:57], v[6:7]
	v_mov_b64_e32 v[54:55], v[4:5]
	v_mov_b64_e32 v[52:53], v[2:3]
	v_mov_b64_e32 v[50:51], v[0:1]
	v_mov_b64_e32 v[46:47], v[12:13]
	v_mov_b64_e32 v[44:45], v[10:11]
	v_mov_b64_e32 v[42:43], v[8:9]
	v_mov_b64_e32 v[40:41], v[6:7]
	v_mov_b64_e32 v[38:39], v[4:5]
	v_mov_b64_e32 v[36:37], v[2:3]
	v_mov_b64_e32 v[34:35], v[0:1]
	v_mov_b64_e32 v[30:31], v[12:13]
	v_mov_b64_e32 v[28:29], v[10:11]
	v_mov_b64_e32 v[26:27], v[8:9]
	v_mov_b64_e32 v[24:25], v[6:7]
	v_mov_b64_e32 v[22:23], v[4:5]
	v_mov_b64_e32 v[20:21], v[2:3]
	v_mov_b64_e32 v[18:19], v[0:1]
	v_mov_b64_e32 v[16:17], v[14:15]
	s_xor_b64 s[2:3], s[8:9], -1
	s_add_i32 s79, s33, 2
	s_mov_b32 s99, 0
	v_mov_b32_e32 v233, 0xf149f2ca
	v_mov_b32_e32 v232, 0
	s_movk_i32 s98, 0xff
	v_mov_b64_e32 v[200:201], v[198:199]
	v_mov_b64_e32 v[14:15], v[12:13]
	v_mov_b64_e32 v[12:13], v[10:11]
	v_mov_b64_e32 v[10:11], v[8:9]
	v_mov_b64_e32 v[8:9], v[6:7]
	v_mov_b64_e32 v[6:7], v[4:5]
	v_mov_b64_e32 v[4:5], v[2:3]
	v_mov_b64_e32 v[2:3], v[0:1]
	s_waitcnt lgkmcnt(0)
	s_barrier
	s_cmp_lt_u32 s97, 64
	s_cbranch_scc1 .Lattn_prio_skip
	s_setprio 2
.Lattn_prio_skip:
	s_cmp_lt_u32 s99, s33
	s_cselect_b64 s[38:39], -1, 0
	s_cmp_ge_u32 s99, s33
	s_cbranch_scc1 .LBB0_167
	s_branch .LBB0_166

.LBB0_207:
	s_add_i32 s10, s99, 4
	s_mov_b64 s[8:9], 0x180000
	s_addk_i32 s98, 0x100
	v_lshl_add_u64 v[200:201], v[200:201], 0, s[8:9]
	s_cmp_gt_u32 s10, s33
	v_add_u32_e32 v231, 0xffffff00, v231
	s_cbranch_scc0 .LBB0_165
	s_setprio 0
	s_and_saveexec_b64 s[8:9], s[4:5]
	ds_write_b32 v159, v232
	s_or_b64 exec, exec, s[8:9]
	s_waitcnt lgkmcnt(0)
	ds_read_b128 v[70:73], v161
	ds_read_b128 v[66:69], v161 offset:32
	s_mov_b32 s98, s0
	s_mov_b32 s79, s94
	s_mov_b32 s99, s1
	s_waitcnt lgkmcnt(1)
	v_div_scale_f32 v1, s[8:9], v70, v70, 1.0
	v_rcp_f32_e32 v74, v1
	s_nop 0
	v_fma_f32 v75, -v1, v74, 1.0
	v_fmac_f32_e32 v74, v75, v74
	v_div_scale_f32 v75, vcc, 1.0, v70, 1.0
	v_mul_f32_e32 v76, v75, v74
	v_fma_f32 v77, -v1, v76, v75
	v_fmac_f32_e32 v76, v77, v74
	v_fma_f32 v1, -v1, v76, v75
	v_div_fmas_f32 v1, v1, v74, v76
	v_div_fixup_f32 v96, v1, v70, 1.0
	v_div_scale_f32 v1, s[8:9], v71, v71, 1.0
	v_rcp_f32_e32 v70, v1
	s_nop 0
	v_fma_f32 v74, -v1, v70, 1.0
	v_fmac_f32_e32 v70, v74, v70
	v_div_scale_f32 v74, vcc, 1.0, v71, 1.0
	v_mul_f32_e32 v75, v74, v70
	v_fma_f32 v76, -v1, v75, v74
	v_fmac_f32_e32 v75, v76, v70
	v_fma_f32 v1, -v1, v75, v74
	v_div_fmas_f32 v1, v1, v70, v75
	v_div_fixup_f32 v94, v1, v71, 1.0
	v_div_scale_f32 v1, s[8:9], v72, v72, 1.0
	v_rcp_f32_e32 v70, v1
	s_nop 0
	v_fma_f32 v71, -v1, v70, 1.0
	v_fmac_f32_e32 v70, v71, v70
	v_div_scale_f32 v71, vcc, 1.0, v72, 1.0
	v_mul_f32_e32 v74, v71, v70
	v_fma_f32 v75, -v1, v74, v71
	v_fmac_f32_e32 v74, v75, v70
	v_fma_f32 v1, -v1, v74, v71
	v_div_fmas_f32 v1, v1, v70, v74
	v_div_fixup_f32 v92, v1, v72, 1.0
	v_div_scale_f32 v1, s[8:9], v73, v73, 1.0
	v_rcp_f32_e32 v70, v1
	s_nop 0
	v_fma_f32 v71, -v1, v70, 1.0
	v_fmac_f32_e32 v70, v71, v70
	v_div_scale_f32 v71, vcc, 1.0, v73, 1.0
	v_mul_f32_e32 v72, v71, v70
	v_fma_f32 v74, -v1, v72, v71
	v_fmac_f32_e32 v72, v74, v70
	v_fma_f32 v1, -v1, v72, v71
	v_div_fmas_f32 v1, v1, v70, v72
	v_div_fixup_f32 v90, v1, v73, 1.0
	s_waitcnt lgkmcnt(0)
	v_div_scale_f32 v1, s[8:9], v66, v66, 1.0
	v_rcp_f32_e32 v70, v1
	s_nop 0
	v_fma_f32 v71, -v1, v70, 1.0
	v_fmac_f32_e32 v70, v71, v70
	v_div_scale_f32 v71, vcc, 1.0, v66, 1.0
	v_mul_f32_e32 v72, v71, v70
	v_fma_f32 v73, -v1, v72, v71
	v_fmac_f32_e32 v72, v73, v70
	v_fma_f32 v1, -v1, v72, v71
	v_div_fmas_f32 v1, v1, v70, v72
	v_div_fixup_f32 v88, v1, v66, 1.0
	v_div_scale_f32 v1, s[8:9], v67, v67, 1.0
	v_rcp_f32_e32 v66, v1
	s_nop 0
	v_fma_f32 v70, -v1, v66, 1.0
	v_fmac_f32_e32 v66, v70, v66
	v_div_scale_f32 v70, vcc, 1.0, v67, 1.0
	v_mul_f32_e32 v71, v70, v66
	v_fma_f32 v72, -v1, v71, v70
	v_fmac_f32_e32 v71, v72, v66
	v_fma_f32 v1, -v1, v71, v70
	v_div_fmas_f32 v1, v1, v66, v71
	v_div_fixup_f32 v86, v1, v67, 1.0
	v_div_scale_f32 v1, s[8:9], v68, v68, 1.0
	v_rcp_f32_e32 v66, v1
	s_nop 0
	v_fma_f32 v67, -v1, v66, 1.0
	v_fmac_f32_e32 v66, v67, v66
	v_div_scale_f32 v67, vcc, 1.0, v68, 1.0
	v_mul_f32_e32 v70, v67, v66
	v_fma_f32 v71, -v1, v70, v67
	v_fmac_f32_e32 v70, v71, v66
	v_fma_f32 v1, -v1, v70, v67
	v_div_fmas_f32 v1, v1, v66, v70
	v_div_fixup_f32 v84, v1, v68, 1.0
	v_div_scale_f32 v1, s[8:9], v69, v69, 1.0
	v_rcp_f32_e32 v66, v1
	s_nop 0
	v_fma_f32 v67, -v1, v66, 1.0
	v_fmac_f32_e32 v66, v67, v66
	v_div_scale_f32 v67, vcc, 1.0, v69, 1.0
	v_mul_f32_e32 v68, v67, v66
	v_fma_f32 v70, -v1, v68, v67
	v_fmac_f32_e32 v68, v70, v66
	v_fma_f32 v1, -v1, v68, v67
	v_div_fmas_f32 v1, v1, v66, v68
	v_div_fixup_f32 v82, v1, v69, 1.0
	ds_read_b128 v[66:69], v161 offset:64
	s_waitcnt lgkmcnt(0)
	v_div_scale_f32 v1, s[8:9], v66, v66, 1.0
	v_rcp_f32_e32 v70, v1
	s_nop 0
	v_fma_f32 v71, -v1, v70, 1.0
	v_fmac_f32_e32 v70, v71, v70
	v_div_scale_f32 v71, vcc, 1.0, v66, 1.0
	v_mul_f32_e32 v72, v71, v70
	v_fma_f32 v73, -v1, v72, v71
	v_fmac_f32_e32 v72, v73, v70
	v_fma_f32 v1, -v1, v72, v71
	v_div_fmas_f32 v1, v1, v70, v72
	v_div_fixup_f32 v80, v1, v66, 1.0
	v_div_scale_f32 v1, s[8:9], v67, v67, 1.0
	v_rcp_f32_e32 v66, v1
	s_nop 0
	v_fma_f32 v70, -v1, v66, 1.0
	v_fmac_f32_e32 v66, v70, v66
	v_div_scale_f32 v70, vcc, 1.0, v67, 1.0
	v_mul_f32_e32 v71, v70, v66
	v_fma_f32 v72, -v1, v71, v70
	v_fmac_f32_e32 v71, v72, v66
	v_fma_f32 v1, -v1, v71, v70
	v_div_fmas_f32 v1, v1, v66, v71
	v_div_fixup_f32 v76, v1, v67, 1.0
	v_div_scale_f32 v1, s[8:9], v68, v68, 1.0
	v_rcp_f32_e32 v66, v1
	s_nop 0
	v_fma_f32 v67, -v1, v66, 1.0
	v_fmac_f32_e32 v66, v67, v66
	v_div_scale_f32 v67, vcc, 1.0, v68, 1.0
	v_mul_f32_e32 v70, v67, v66
	v_fma_f32 v71, -v1, v70, v67
	v_fmac_f32_e32 v70, v71, v66
	v_fma_f32 v1, -v1, v70, v67
	v_div_fmas_f32 v1, v1, v66, v70
	v_div_fixup_f32 v72, v1, v68, 1.0
	v_div_scale_f32 v1, s[8:9], v69, v69, 1.0
	v_rcp_f32_e32 v66, v1
	s_nop 0
	v_fma_f32 v67, -v1, v66, 1.0
	v_fmac_f32_e32 v66, v67, v66
	v_div_scale_f32 v67, vcc, 1.0, v69, 1.0
	v_mul_f32_e32 v68, v67, v66
	v_fma_f32 v70, -v1, v68, v67
	v_fmac_f32_e32 v68, v70, v66
	v_fma_f32 v1, -v1, v68, v67
	v_div_fmas_f32 v1, v1, v66, v68
	v_div_fixup_f32 v70, v1, v69, 1.0
	ds_read_b128 v[66:69], v161 offset:96
	s_waitcnt lgkmcnt(0)
	v_div_scale_f32 v1, s[8:9], v66, v66, 1.0
	v_rcp_f32_e32 v71, v1
	s_nop 0
	v_fma_f32 v73, -v1, v71, 1.0
	v_fmac_f32_e32 v71, v73, v71
	v_div_scale_f32 v73, vcc, 1.0, v66, 1.0
	v_mul_f32_e32 v74, v73, v71
	v_fma_f32 v75, -v1, v74, v73
	v_fmac_f32_e32 v74, v75, v71
	v_fma_f32 v1, -v1, v74, v73
	v_div_fmas_f32 v1, v1, v71, v74
	v_div_fixup_f32 v78, v1, v66, 1.0
	v_div_scale_f32 v1, s[8:9], v67, v67, 1.0
	v_rcp_f32_e32 v66, v1
	s_nop 0
	v_fma_f32 v71, -v1, v66, 1.0
	v_fmac_f32_e32 v66, v71, v66
	v_div_scale_f32 v71, vcc, 1.0, v67, 1.0
	v_mul_f32_e32 v73, v71, v66
	v_fma_f32 v74, -v1, v73, v71
	v_fmac_f32_e32 v73, v74, v66
	v_fma_f32 v1, -v1, v73, v71
	v_div_fmas_f32 v1, v1, v66, v73
	v_div_fixup_f32 v74, v1, v67, 1.0
	v_div_scale_f32 v1, s[8:9], v68, v68, 1.0
	v_rcp_f32_e32 v66, v1
	s_nop 0
	v_fma_f32 v67, -v1, v66, 1.0
	v_fmac_f32_e32 v66, v67, v66
	v_div_scale_f32 v67, vcc, 1.0, v68, 1.0
	v_mul_f32_e32 v71, v67, v66
	v_fma_f32 v73, -v1, v71, v67
	v_fmac_f32_e32 v71, v73, v66
	v_fma_f32 v1, -v1, v71, v67
	v_div_fmas_f32 v1, v1, v66, v71
	v_div_fixup_f32 v68, v1, v68, 1.0
	v_div_scale_f32 v1, s[8:9], v69, v69, 1.0
	v_rcp_f32_e32 v66, v1
	s_nop 0
	v_fma_f32 v67, -v1, v66, 1.0
	v_fmac_f32_e32 v66, v67, v66
	v_div_scale_f32 v67, vcc, 1.0, v69, 1.0
	v_mul_f32_e32 v71, v67, v66
	v_fma_f32 v73, -v1, v71, v67
	v_fmac_f32_e32 v71, v73, v66
	v_fma_f32 v1, -v1, v71, v67
	v_div_fmas_f32 v1, v1, v66, v71
	v_div_fixup_f32 v66, v1, v69, 1.0
	s_andn2_b64 vcc, exec, s[76:77]
	s_cbranch_vccnz .LBB0_212
	v_mul_f32_e32 v1, v50, v96
	v_mul_f32_e32 v67, v34, v96
	v_mul_f32_e32 v1, v151, v1
	v_mul_f32_e32 v67, v151, v67
	ds_write2_b32 v163, v1, v67 offset1:32
	v_mul_f32_e32 v1, v18, v96
	v_mul_f32_e32 v67, v2, v96
	v_mul_f32_e32 v1, v151, v1
	v_mul_f32_e32 v67, v151, v67
	ds_write2_b32 v163, v1, v67 offset0:64 offset1:96
	v_mul_f32_e32 v1, v51, v94
	v_mul_f32_e32 v67, v35, v94
	v_mul_f32_e32 v1, v151, v1
	v_mul_f32_e32 v67, v151, v67
	ds_write2_b32 v163, v1, v67 offset0:128 offset1:160
	v_mul_f32_e32 v1, v19, v94
	v_mul_f32_e32 v67, v3, v94
	v_mul_f32_e32 v1, v151, v1
	v_mul_f32_e32 v67, v151, v67
	ds_write2_b32 v163, v1, v67 offset0:192 offset1:224
	v_mul_f32_e32 v1, v52, v92
	v_mul_f32_e32 v67, v36, v92
	v_mul_f32_e32 v1, v151, v1
	v_mul_f32_e32 v67, v151, v67
	v_add_u32_e32 v69, 0x400, v163
	ds_write2_b32 v69, v1, v67 offset1:32
	v_mul_f32_e32 v1, v20, v92
	v_mul_f32_e32 v67, v4, v92
	v_mul_f32_e32 v1, v151, v1
	v_mul_f32_e32 v67, v151, v67
	ds_write2_b32 v69, v1, v67 offset0:64 offset1:96
	v_mul_f32_e32 v1, v53, v90
	v_mul_f32_e32 v67, v37, v90
	v_mul_f32_e32 v1, v151, v1
	v_mul_f32_e32 v67, v151, v67
	ds_write2_b32 v69, v1, v67 offset0:128 offset1:160
	v_mul_f32_e32 v1, v21, v90
	v_mul_f32_e32 v67, v5, v90
	v_mul_f32_e32 v1, v151, v1
	v_mul_f32_e32 v67, v151, v67
	ds_write2_b32 v69, v1, v67 offset0:192 offset1:224
	v_mul_f32_e32 v1, v54, v88
	v_mul_f32_e32 v67, v38, v88
	v_mul_f32_e32 v1, v151, v1
	v_mul_f32_e32 v67, v151, v67
	v_add_u32_e32 v69, 0x1000, v163
	ds_write2_b32 v69, v1, v67 offset1:32
	v_mul_f32_e32 v1, v22, v88
	v_mul_f32_e32 v67, v6, v88
	v_mul_f32_e32 v1, v151, v1
	v_mul_f32_e32 v67, v151, v67
	ds_write2_b32 v69, v1, v67 offset0:64 offset1:96
	v_mul_f32_e32 v1, v55, v86
	v_mul_f32_e32 v67, v39, v86
	v_mul_f32_e32 v1, v151, v1
	v_mul_f32_e32 v67, v151, v67
	ds_write2_b32 v69, v1, v67 offset0:128 offset1:160
	v_mul_f32_e32 v1, v23, v86
	v_mul_f32_e32 v67, v7, v86
	v_mul_f32_e32 v1, v151, v1
	v_mul_f32_e32 v67, v151, v67
	ds_write2_b32 v69, v1, v67 offset0:192 offset1:224
	v_mul_f32_e32 v1, v56, v84
	v_mul_f32_e32 v67, v40, v84
	v_mul_f32_e32 v1, v151, v1
	v_mul_f32_e32 v67, v151, v67
	v_add_u32_e32 v69, 0x1400, v163
	ds_write2_b32 v69, v1, v67 offset1:32
	v_mul_f32_e32 v1, v24, v84
	v_mul_f32_e32 v67, v8, v84
	v_mul_f32_e32 v1, v151, v1
	v_mul_f32_e32 v67, v151, v67
	ds_write2_b32 v69, v1, v67 offset0:64 offset1:96
	v_mul_f32_e32 v1, v57, v82
	v_mul_f32_e32 v67, v41, v82
	v_mul_f32_e32 v1, v151, v1
	v_mul_f32_e32 v67, v151, v67
	ds_write2_b32 v69, v1, v67 offset0:128 offset1:160
	v_mul_f32_e32 v1, v25, v82
	v_mul_f32_e32 v67, v9, v82
	v_mul_f32_e32 v1, v151, v1
	v_mul_f32_e32 v67, v151, v67
	ds_write2_b32 v69, v1, v67 offset0:192 offset1:224
	v_mul_f32_e32 v1, v58, v80
	v_mul_f32_e32 v67, v42, v80
	v_mul_f32_e32 v1, v151, v1
	v_mul_f32_e32 v67, v151, v67
	v_add_u32_e32 v69, 0x2000, v163
	ds_write2_b32 v69, v1, v67 offset1:32
	v_mul_f32_e32 v1, v26, v80
	v_mul_f32_e32 v67, v10, v80
	v_mul_f32_e32 v1, v151, v1
	v_mul_f32_e32 v67, v151, v67
	ds_write2_b32 v69, v1, v67 offset0:64 offset1:96
	v_mul_f32_e32 v1, v59, v76
	v_mul_f32_e32 v67, v43, v76
	v_mul_f32_e32 v1, v151, v1
	v_mul_f32_e32 v67, v151, v67
	ds_write2_b32 v69, v1, v67 offset0:128 offset1:160
	v_mul_f32_e32 v1, v27, v76
	v_mul_f32_e32 v67, v11, v76
	v_mul_f32_e32 v1, v151, v1
	v_mul_f32_e32 v67, v151, v67
	ds_write2_b32 v69, v1, v67 offset0:192 offset1:224
	v_mul_f32_e32 v1, v60, v72
	v_mul_f32_e32 v67, v44, v72
	v_mul_f32_e32 v1, v151, v1
	v_mul_f32_e32 v67, v151, v67
	v_add_u32_e32 v69, 0x2400, v163
	ds_write2_b32 v69, v1, v67 offset1:32
	v_mul_f32_e32 v1, v28, v72
	v_mul_f32_e32 v67, v12, v72
	v_mul_f32_e32 v1, v151, v1
	v_mul_f32_e32 v67, v151, v67
	ds_write2_b32 v69, v1, v67 offset0:64 offset1:96
	v_mul_f32_e32 v1, v61, v70
	v_mul_f32_e32 v67, v45, v70
	v_mul_f32_e32 v1, v151, v1
	v_mul_f32_e32 v67, v151, v67
	ds_write2_b32 v69, v1, v67 offset0:128 offset1:160
	v_mul_f32_e32 v1, v29, v70
	v_mul_f32_e32 v67, v13, v70
	v_mul_f32_e32 v1, v151, v1
	v_mul_f32_e32 v67, v151, v67
	ds_write2_b32 v69, v1, v67 offset0:192 offset1:224
	v_mul_f32_e32 v1, v62, v78
	v_mul_f32_e32 v67, v46, v78
	v_mul_f32_e32 v1, v151, v1
	v_mul_f32_e32 v67, v151, v67
	v_add_u32_e32 v69, 0x3000, v163
	ds_write2_b32 v69, v1, v67 offset1:32
	v_mul_f32_e32 v1, v30, v78
	v_mul_f32_e32 v67, v14, v78
	v_mul_f32_e32 v1, v151, v1
	v_mul_f32_e32 v67, v151, v67
	ds_write2_b32 v69, v1, v67 offset0:64 offset1:96
	v_mul_f32_e32 v1, v63, v74
	v_mul_f32_e32 v67, v47, v74
	v_mul_f32_e32 v1, v151, v1
	v_mul_f32_e32 v67, v151, v67
	ds_write2_b32 v69, v1, v67 offset0:128 offset1:160
	v_mul_f32_e32 v1, v31, v74
	v_mul_f32_e32 v67, v15, v74
	v_mul_f32_e32 v1, v151, v1
	v_mul_f32_e32 v67, v151, v67
	ds_write2_b32 v69, v1, v67 offset0:192 offset1:224
	v_mul_f32_e32 v1, v64, v68
	v_mul_f32_e32 v67, v48, v68
	v_mul_f32_e32 v1, v151, v1
	v_mul_f32_e32 v67, v151, v67
	v_add_u32_e32 v69, 0x3400, v163
	ds_write2_b32 v69, v1, v67 offset1:32
	v_mul_f32_e32 v1, v32, v68
	v_mul_f32_e32 v67, v16, v68
	v_mul_f32_e32 v1, v151, v1
	v_mul_f32_e32 v67, v151, v67
	ds_write2_b32 v69, v1, v67 offset0:64 offset1:96
	v_mul_f32_e32 v1, v65, v66
	v_mul_f32_e32 v67, v49, v66
	v_mul_f32_e32 v1, v151, v1
	v_mul_f32_e32 v67, v151, v67
	ds_write2_b32 v69, v1, v67 offset0:128 offset1:160
	v_mul_f32_e32 v1, v33, v66
	v_mul_f32_e32 v67, v17, v66
	v_mul_f32_e32 v1, v151, v1
	v_mul_f32_e32 v67, v151, v67
	ds_write2_b32 v69, v1, v67 offset0:192 offset1:224
